# E44: grid barrier: the global-last XCD leader bumps every XCD's release word directly after TOPGEN; other leaders no longer forward the release (one hop less for 7 of 8 XCDs); on E41
# speedup vs baseline: 1.0032x; 1.0009x over previous
.LBB0_145:
	s_or_b64 exec, exec, s[18:19]
	v_cvt_f32_u32_e32 v5, v2
	s_waitcnt vmcnt(0)
	v_readfirstlane_b32 s3, v4
	s_add_u32 s18, s82, 0x43500
	s_addc_u32 s19, s83, 0
	v_rcp_iflag_f32_e32 v5, v5
	v_add_u32_e32 v3, s3, v3
	v_add_u32_e32 v6, 1, v3
	s_mov_b64 s[24:25], -1
	v_mul_f32_e32 v4, 0x4f7ffffe, v5
	v_cvt_u32_f32_e32 v4, v4
	v_sub_u32_e32 v5, 0, v2
	v_mul_lo_u32 v5, v5, v4
	v_mul_hi_u32 v5, v4, v5
	v_add_u32_e32 v4, v4, v5
	v_mul_hi_u32 v4, v3, v4
	v_mul_lo_u32 v5, v4, v2
	v_sub_u32_e32 v3, v3, v5
	v_add_u32_e32 v7, 1, v4
	v_cmp_ge_u32_e32 vcc, v3, v2
	v_sub_u32_e32 v5, v3, v2
	s_nop 0
	v_cndmask_b32_e32 v4, v4, v7, vcc
	v_cndmask_b32_e32 v3, v3, v5, vcc
	v_add_u32_e32 v5, 1, v4
	v_cmp_ge_u32_e32 vcc, v3, v2
	s_nop 1
	v_cndmask_b32_e32 v4, v4, v5, vcc
	v_mul_lo_u32 v3, v2, v4
	v_add_u32_e32 v2, v3, v2
	v_cmp_ne_u32_e32 vcc, v6, v2
	v_mov_b64_e32 v[2:3], s[18:19]
	s_mov_b32 s101, 0
	s_and_saveexec_b64 s[16:17], vcc
	s_cbranch_execz .LBB0_157
	s_mov_b32 s101, 1
	v_mov_b32_e32 v2, 0
	global_load_dword v3, v2, s[18:19] sc1
	s_mov_b64 s[28:29], 0
	s_waitcnt vmcnt(0)
	v_cmp_eq_u32_e32 vcc, v3, v4
	s_and_saveexec_b64 s[26:27], vcc
	s_cbranch_execz .LBB0_156
	s_add_u32 s24, s82, 0x40200
	s_addc_u32 s25, s83, 0
	s_mov_b32 s3, 1
	s_branch .LBB0_149

.LBB0_159:
	s_or_b64 exec, exec, s[16:17]
	s_mov_b64 s[16:17], exec
	v_mbcnt_lo_u32_b32 v2, s16, 0
	v_mbcnt_hi_u32_b32 v2, s17, v2
	v_cmp_eq_u32_e32 vcc, 0, v2
	s_waitcnt vmcnt(0)
	s_and_saveexec_b64 s[18:19], vcc
	s_cbranch_execz .LBB0_161
	s_bcnt1_i32_b64 s3, s[16:17]
	s_cmp_lg_u32 s101, 0
	s_cbranch_scc1 .Lxrel_skip0
	v_mov_b32_e32 v2, 0x42400
	v_mov_b32_e32 v3, 1
	global_atomic_add v2, v3, s[82:83]
	global_atomic_add v2, v3, s[82:83] offset:256
	global_atomic_add v2, v3, s[82:83] offset:512
	global_atomic_add v2, v3, s[82:83] offset:768
	global_atomic_add v2, v3, s[82:83] offset:1024
	global_atomic_add v2, v3, s[82:83] offset:1280
	global_atomic_add v2, v3, s[82:83] offset:1536
	global_atomic_add v2, v3, s[82:83] offset:1792
	global_atomic_add v2, v3, s[82:83] offset:2048
	global_atomic_add v2, v3, s[82:83] offset:2304
	global_atomic_add v2, v3, s[82:83] offset:2560
	global_atomic_add v2, v3, s[82:83] offset:2816
	global_atomic_add v2, v3, s[82:83] offset:3072
	global_atomic_add v2, v3, s[82:83] offset:3328
	global_atomic_add v2, v3, s[82:83] offset:3584
	global_atomic_add v2, v3, s[82:83] offset:3840
.Lxrel_skip0:
.LBB0_161:
	s_or_b64 exec, exec, s[18:19]
	s_waitcnt vmcnt(0)

.LBB0_610:
	s_or_b64 exec, exec, s[10:11]
	v_cvt_f32_u32_e32 v6, v3
	s_waitcnt vmcnt(0)
	v_readfirstlane_b32 s3, v5
	s_add_u32 s10, s82, 0x43500
	s_addc_u32 s11, s83, 0
	v_rcp_iflag_f32_e32 v6, v6
	v_add_u32_e32 v4, s3, v4
	v_add_u32_e32 v7, 1, v4
	s_mov_b64 s[12:13], -1
	v_mul_f32_e32 v5, 0x4f7ffffe, v6
	v_cvt_u32_f32_e32 v5, v5
	v_sub_u32_e32 v6, 0, v3
	v_mul_lo_u32 v6, v6, v5
	v_mul_hi_u32 v6, v5, v6
	v_add_u32_e32 v5, v5, v6
	v_mul_hi_u32 v5, v4, v5
	v_mul_lo_u32 v6, v5, v3
	v_sub_u32_e32 v4, v4, v6
	v_add_u32_e32 v8, 1, v5
	v_cmp_ge_u32_e32 vcc, v4, v3
	v_sub_u32_e32 v6, v4, v3
	s_nop 0
	v_cndmask_b32_e32 v5, v5, v8, vcc
	v_cndmask_b32_e32 v4, v4, v6, vcc
	v_add_u32_e32 v6, 1, v5
	v_cmp_ge_u32_e32 vcc, v4, v3
	s_nop 1
	v_cndmask_b32_e32 v6, v5, v6, vcc
	v_mul_lo_u32 v4, v3, v6
	v_add_u32_e32 v3, v4, v3
	v_cmp_ne_u32_e32 vcc, v7, v3
	v_mov_b64_e32 v[4:5], s[10:11]
	s_mov_b32 s101, 0
	s_and_saveexec_b64 s[8:9], vcc
	s_cbranch_execz .LBB0_622
	s_mov_b32 s101, 1
	v_mov_b32_e32 v3, 0
	global_load_dword v4, v3, s[10:11] sc1
	s_mov_b64 s[18:19], 0
	s_waitcnt vmcnt(0)
	v_cmp_eq_u32_e32 vcc, v4, v6
	s_and_saveexec_b64 s[16:17], vcc
	s_cbranch_execz .LBB0_621
	s_add_u32 s12, s82, 0x40200
	s_addc_u32 s13, s83, 0
	s_mov_b32 s3, 1
	s_branch .LBB0_614

.LBB0_624:
	s_or_b64 exec, exec, s[8:9]
	s_mov_b64 s[8:9], exec
	v_mbcnt_lo_u32_b32 v3, s8, 0
	v_mbcnt_hi_u32_b32 v3, s9, v3
	v_cmp_eq_u32_e32 vcc, 0, v3
	s_waitcnt vmcnt(0)
	s_and_saveexec_b64 s[10:11], vcc
	s_cbranch_execz .LBB0_626
	s_bcnt1_i32_b64 s3, s[8:9]
	s_cmp_lg_u32 s101, 0
	s_cbranch_scc1 .Lxrel_skip2
	v_mov_b32_e32 v3, 0x42400
	v_mov_b32_e32 v4, 1
	global_atomic_add v3, v4, s[82:83]
	global_atomic_add v3, v4, s[82:83] offset:256
	global_atomic_add v3, v4, s[82:83] offset:512
	global_atomic_add v3, v4, s[82:83] offset:768
	global_atomic_add v3, v4, s[82:83] offset:1024
	global_atomic_add v3, v4, s[82:83] offset:1280
	global_atomic_add v3, v4, s[82:83] offset:1536
	global_atomic_add v3, v4, s[82:83] offset:1792
	global_atomic_add v3, v4, s[82:83] offset:2048
	global_atomic_add v3, v4, s[82:83] offset:2304
	global_atomic_add v3, v4, s[82:83] offset:2560
	global_atomic_add v3, v4, s[82:83] offset:2816
	global_atomic_add v3, v4, s[82:83] offset:3072
	global_atomic_add v3, v4, s[82:83] offset:3328
	global_atomic_add v3, v4, s[82:83] offset:3584
	global_atomic_add v3, v4, s[82:83] offset:3840
.Lxrel_skip2:
.LBB0_626:
	s_or_b64 exec, exec, s[10:11]
	s_waitcnt vmcnt(0)

.LBB0_1206:
	s_or_b64 exec, exec, s[10:11]
	v_cvt_f32_u32_e32 v6, v3
	s_waitcnt vmcnt(0)
	v_readfirstlane_b32 s3, v5
	s_add_u32 s10, s82, 0x43500
	s_addc_u32 s11, s83, 0
	v_rcp_iflag_f32_e32 v6, v6
	v_add_u32_e32 v4, s3, v4
	v_add_u32_e32 v7, 1, v4
	s_mov_b64 s[12:13], -1
	v_mul_f32_e32 v5, 0x4f7ffffe, v6
	v_cvt_u32_f32_e32 v5, v5
	v_sub_u32_e32 v6, 0, v3
	v_mul_lo_u32 v6, v6, v5
	v_mul_hi_u32 v6, v5, v6
	v_add_u32_e32 v5, v5, v6
	v_mul_hi_u32 v5, v4, v5
	v_mul_lo_u32 v6, v5, v3
	v_sub_u32_e32 v4, v4, v6
	v_add_u32_e32 v8, 1, v5
	v_cmp_ge_u32_e32 vcc, v4, v3
	v_sub_u32_e32 v6, v4, v3
	s_nop 0
	v_cndmask_b32_e32 v5, v5, v8, vcc
	v_cndmask_b32_e32 v4, v4, v6, vcc
	v_add_u32_e32 v6, 1, v5
	v_cmp_ge_u32_e32 vcc, v4, v3
	s_nop 1
	v_cndmask_b32_e32 v6, v5, v6, vcc
	v_mul_lo_u32 v4, v3, v6
	v_add_u32_e32 v3, v4, v3
	v_cmp_ne_u32_e32 vcc, v7, v3
	v_mov_b64_e32 v[4:5], s[10:11]
	s_mov_b32 s101, 0
	s_and_saveexec_b64 s[8:9], vcc
	s_cbranch_execz .LBB0_1218
	s_mov_b32 s101, 1
	v_mov_b32_e32 v3, 0
	global_load_dword v4, v3, s[10:11] sc1
	s_mov_b64 s[16:17], 0
	s_waitcnt vmcnt(0)
	v_cmp_eq_u32_e32 vcc, v4, v6
	s_and_saveexec_b64 s[14:15], vcc
	s_cbranch_execz .LBB0_1217
	s_add_u32 s12, s82, 0x40200
	s_addc_u32 s13, s83, 0
	s_mov_b32 s3, 1
	s_branch .LBB0_1210

.LBB0_1543:
	s_or_b64 exec, exec, s[10:11]
	v_cvt_f32_u32_e32 v5, v2
	s_waitcnt vmcnt(0)
	v_readfirstlane_b32 s3, v4
	s_add_u32 s10, s82, 0x43500
	s_addc_u32 s11, s83, 0
	v_rcp_iflag_f32_e32 v5, v5
	v_add_u32_e32 v3, s3, v3
	v_add_u32_e32 v6, 1, v3
	s_mov_b64 s[12:13], -1
	v_mul_f32_e32 v4, 0x4f7ffffe, v5
	v_cvt_u32_f32_e32 v4, v4
	v_sub_u32_e32 v5, 0, v2
	v_mul_lo_u32 v5, v5, v4
	v_mul_hi_u32 v5, v4, v5
	v_add_u32_e32 v4, v4, v5
	v_mul_hi_u32 v4, v3, v4
	v_mul_lo_u32 v5, v4, v2
	v_sub_u32_e32 v3, v3, v5
	v_add_u32_e32 v7, 1, v4
	v_cmp_ge_u32_e32 vcc, v3, v2
	v_sub_u32_e32 v5, v3, v2
	s_nop 0
	v_cndmask_b32_e32 v4, v4, v7, vcc
	v_cndmask_b32_e32 v3, v3, v5, vcc
	v_add_u32_e32 v5, 1, v4
	v_cmp_ge_u32_e32 vcc, v3, v2
	s_nop 1
	v_cndmask_b32_e32 v4, v4, v5, vcc
	v_mul_lo_u32 v3, v2, v4
	v_add_u32_e32 v2, v3, v2
	v_cmp_ne_u32_e32 vcc, v6, v2
	v_mov_b64_e32 v[2:3], s[10:11]
	s_mov_b32 s101, 0
	s_and_saveexec_b64 s[8:9], vcc
	s_cbranch_execz .LBB0_1555
	s_mov_b32 s101, 1
	v_mov_b32_e32 v2, 0
	global_load_dword v3, v2, s[10:11] sc1
	s_mov_b64 s[16:17], 0
	s_waitcnt vmcnt(0)
	v_cmp_eq_u32_e32 vcc, v3, v4
	s_and_saveexec_b64 s[14:15], vcc
	s_cbranch_execz .LBB0_1554
	s_add_u32 s12, s82, 0x40200
	s_addc_u32 s13, s83, 0
	s_mov_b32 s3, 1
	s_branch .LBB0_1547

.LBB0_1557:
	s_or_b64 exec, exec, s[8:9]
	s_mov_b64 s[8:9], exec
	v_mbcnt_lo_u32_b32 v2, s8, 0
	v_mbcnt_hi_u32_b32 v2, s9, v2
	v_cmp_eq_u32_e32 vcc, 0, v2
	s_waitcnt vmcnt(0)
	s_and_saveexec_b64 s[10:11], vcc
	s_cbranch_execz .LBB0_1559
	s_bcnt1_i32_b64 s3, s[8:9]
	s_cmp_lg_u32 s101, 0
	s_cbranch_scc1 .Lxrel_skip7
	v_mov_b32_e32 v2, 0x42400
	v_mov_b32_e32 v3, 1
	global_atomic_add v2, v3, s[82:83]
	global_atomic_add v2, v3, s[82:83] offset:256
	global_atomic_add v2, v3, s[82:83] offset:512
	global_atomic_add v2, v3, s[82:83] offset:768
	global_atomic_add v2, v3, s[82:83] offset:1024
	global_atomic_add v2, v3, s[82:83] offset:1280
	global_atomic_add v2, v3, s[82:83] offset:1536
	global_atomic_add v2, v3, s[82:83] offset:1792
	global_atomic_add v2, v3, s[82:83] offset:2048
	global_atomic_add v2, v3, s[82:83] offset:2304
	global_atomic_add v2, v3, s[82:83] offset:2560
	global_atomic_add v2, v3, s[82:83] offset:2816
	global_atomic_add v2, v3, s[82:83] offset:3072
	global_atomic_add v2, v3, s[82:83] offset:3328
	global_atomic_add v2, v3, s[82:83] offset:3584
	global_atomic_add v2, v3, s[82:83] offset:3840
